# band attention: rotate per-unit key-chunk order (chunk X in slot X mod 12) for L2 sharing between units
# baseline (speedup 1.0000x reference)
; #define BISSUE(j_) do { LAS unsigned char* d_ = lds + ((j_) & (D - 1)) * STG + w * 1024; \
;         __builtin_amdgcn_global_load_lds((const unsigned*)((const char*)Kg + (size_t)(j_) * 65536 + goff), (LAS unsigned*)d_, 16, 0, 0); \
;         __builtin_amdgcn_global_load_lds((const unsigned*)((const char*)Vg + (size_t)(j_) * 65536 + goff), (LAS unsigned*)(d_ + 8192), 16, 0, 0); } while (0)
; template <int D>
; __device__ __forceinline__ void band_unit(LAS unsigned char* lds, const bf16_t* Kg, const bf16_t* Vg, const int ntile, const bf16_t* Qg, bf16_t* Og, float* ssa, const int nci, const int crel0, const LAS float* tb) {
;     ...
;     const int drow = 4 * w + (lane >> 4), fdr = ((drow & 3) << 2) | ((drow >> 2) & 3);
;     const size_t goff = (size_t)drow * 2048 + (size_t)(((lane & 15) ^ fdr) << 4);
;     ...
;     bf16x8 qf[8];
;     if (wact) { const bf16_t* qp = Qg + (size_t)(64 * ci + 32 * qb + l31) * 1024 + 8 * hi;
; #pragma unroll
;         for (int i = 0; i < 8; ++i) qf[i] = *(const bf16x8*)(qp + 16 * i); }
;     else {
; #pragma unroll
;         for (int i = 0; i < 8; ++i) qf[i] = (bf16x8){0, 0, 0, 0, 0, 0, 0, 0}; }
; #pragma unroll
;     for (int j = 0; j < 4; ++j) if (j < ntile) BISSUE(j);
; __global__ void __launch_bounds__(512, 2) fwd_kernel(Args a) {
;     ...
;             if (un < 1024) { const int h = un & 7, bg = un >> 3, b = bg >> 5, c0 = (bg & 31) * 4, klo = c0 > 8 ? c0 - 8 : 0;
;                 const size_t krow0 = (size_t)b * SEQ + 64 * klo, qrow0 = (size_t)b * SEQ + 64 * c0;
;                 band_unit<8>(lds, KA + krow0 * 1024 + h * 128, VA + krow0 * 1024 + h * 128, 2 * (c0 + 4 - klo), QB + qrow0 * 1024 + h * 128, MIX + qrow0 * DM + h * 128, SSA + qrow0 * 8 + h, 4, c0 - klo, btab + h * 264); }
.LBB0_588:
	v_sub_u32_e64 v0, s63, 8 clamp
	s_lshr_b32 s60, s59, 6
	v_readfirstlane_b32 s61, v0
	s_lshl_b32 s59, s61, 6
	s_or_b32 s50, s50, s59
	s_lshl_b64 s[50:51], s[50:51], 11
	v_readlane_b32 s12, v243, 33
	v_readlane_b32 s13, v243, 34
	s_add_u32 s62, s12, s50
	s_addc_u32 s64, s13, s51
	s_lshl_b32 s59, s8, 1
	s_add_u32 s66, s62, s59
	s_addc_u32 s67, s64, 0
	s_add_u32 s8, s10, s50
	s_addc_u32 s50, s11, s51
	s_add_u32 s68, s8, s59
	s_addc_u32 s69, s50, 0
	s_lshl_b32 s64, s60, 2
	v_or_b32_e32 v0, s64, v138
	s_and_b32 s50, s60, 3
	s_sub_i32 s8, s63, s61
	v_lshlrev_b64 v[4:5], 11, v[0:1]
	v_bitop3_b32 v0, s50, v140, v139 bitop3:0x36
	s_lshl_b32 s50, s60, 10
	s_add_i32 s8, s8, 4
	s_lshr_b32 s98, s61, 2
	s_mul_i32 s99, s98, 0xaaab
	s_lshr_b32 s99, s99, 17
	s_mul_i32 s99, s99, 3
	s_sub_u32 s98, s98, s99
	s_sub_u32 s98, 3, s98
	s_cmp_eq_u32 s98, 3
	s_cselect_b32 s98, 0, s98
	s_lshl_b32 s100, s98, 19
	s_cmp_eq_u32 s8, 12
	s_cselect_b32 s100, s100, 0
	s_mov_b32 s101, 0
	v_lshlrev_b32_e32 v0, 4, v0
	s_add_i32 s62, s50, 0
	v_or_b32_e32 v4, v4, v0
	s_cmp_gt_i32 s8, 0
	v_lshl_add_u64 v[2:3], s[66:67], 0, v[4:5]
	s_cselect_b64 s[50:51], -1, 0
	s_cmp_lt_i32 s8, 1
	v_lshl_add_u64 v[4:5], s[68:69], 0, v[4:5]
	v_lshl_add_u64 v[2:3], v[2:3], 0, s[100:101]
	v_lshl_add_u64 v[4:5], v[4:5], 0, s[100:101]
	s_cbranch_scc1 .LBB0_590
	s_mov_b32 m0, s62
	s_add_i32 s65, s62, 0x2000
	global_load_lds_dwordx4 v[2:3], off
	s_mov_b32 m0, s65
	s_add_i32 s65, s62, 0x6000
	global_load_lds_dwordx4 v[4:5], off
	v_lshl_add_u64 v[8:9], v[2:3], 0, s[20:21]
	s_add_i32 m0, s62, 0x4000
	v_lshl_add_u64 v[6:7], v[4:5], 0, s[20:21]
	global_load_lds_dwordx4 v[8:9], off
	s_mov_b32 m0, s65
	s_nop 0
	global_load_lds_dwordx4 v[6:7], off

; #define BISSUE(j_) do { LAS unsigned char* d_ = lds + ((j_) & (D - 1)) * STG + w * 1024; \
;         __builtin_amdgcn_global_load_lds((const unsigned*)((const char*)Kg + (size_t)(j_) * 65536 + goff), (LAS unsigned*)d_, 16, 0, 0); \
;         __builtin_amdgcn_global_load_lds((const unsigned*)((const char*)Vg + (size_t)(j_) * 65536 + goff), (LAS unsigned*)(d_ + 8192), 16, 0, 0); } while (0)
; template <int D>
; __device__ __forceinline__ void band_unit(LAS unsigned char* lds, const bf16_t* Kg, const bf16_t* Vg, const int ntile, const bf16_t* Qg, bf16_t* Og, float* ssa, const int nci, const int crel0, const LAS float* tb) {
;     ...
;     for (int j = 0; j < ntile; ++j) {
;         if ((j & 3) == 0) {
;             asm volatile("s_waitcnt vmcnt(0)" ::: "memory");
;             __builtin_amdgcn_s_barrier(); asm volatile("" ::: "memory");
; #pragma unroll
;             for (int jj = 4; jj < 8; ++jj) if (j + jj < ntile) BISSUE(j + jj);
;         }
;         const int kcrel = crel0 + ci - (j >> 1);
.LBB0_595:
	s_add_u32 s100, s100, 0x10000
	s_cmp_eq_u32 s100, s8
	s_cselect_b32 s100, 0, s100
	s_addk_i32 s14, 0x4000
	s_add_u32 s44, s44, 0x10000
	s_addc_u32 s45, s45, 0
	s_add_i32 s64, s64, 1
	s_add_i32 s65, s65, 32
	s_cmp_eq_u32 s8, s44
	s_cbranch_scc1 .LBB0_609
.LBB0_596:
	s_add_i32 s66, s64, -7
	s_and_b32 s67, s66, 3
	s_cmp_lg_u32 s67, 0
	s_cbranch_scc1 .LBB0_605
	s_waitcnt vmcnt(0)
	s_barrier
	s_add_u32 s98, s100, 0x40000
	s_cmp_ge_u32 s98, s8
	s_cselect_b32 s98, s8, 0
	s_sub_u32 s98, s100, s98
	s_subb_u32 s99, 0, 0
	s_add_i32 s67, s64, -3
	s_cmp_ge_u32 s67, s50
	v_lshl_add_u64 v[68:69], v[120:121], 0, s[98:99]
	s_cbranch_scc1 .LBB0_601
	s_add_i32 s67, s14, 0xffff4000
	s_and_b32 s67, s67, 0x10000
	s_mov_b64 s[68:69], 0x18240000
	s_add_i32 s67, s62, s67
	v_lshl_add_u64 v[70:71], v[68:69], 0, s[68:69]
	s_mov_b64 s[68:69], 0x11e40000
	s_add_i32 s70, s67, 0x2000
	v_lshl_add_u64 v[72:73], v[68:69], 0, s[68:69]
	s_mov_b32 m0, s67
	s_nop 0
	global_load_lds_dwordx4 v[72:73], off
	s_mov_b32 m0, s70
	s_nop 0
	global_load_lds_dwordx4 v[70:71], off
	s_add_i32 s67, s64, -2
	s_cmp_ge_u32 s67, s50
	s_cbranch_scc0 .LBB0_602

; #define LAS __attribute__((address_space(3)))
; template <int D>
; __device__ __forceinline__ void band_unit(LAS unsigned char* lds, const bf16_t* Kg, const bf16_t* Vg, const int ntile, const bf16_t* Qg, bf16_t* Og, float* ssa, const int nci, const int crel0, const LAS float* tb) {
;     ...
;         const int kcrel = crel0 + ci - (j >> 1);
;         if (wact && kcrel >= 0 && kcrel <= 8) {
;             const LAS unsigned char* st = lds + (j & (D - 1)) * STG;
;             f32x16 sc;
;             if (kcrel < 3) { const int dbase = 64 * kcrel - 32 * (j & 1) + qb * 32 + l31 - 4 * hi;
; #pragma unroll
;                 for (int r = 0; r < 16; ++r) { int d = dbase - ((r & 3) + 8 * (r >> 2)); d = d > 128 ? 128 : d; sc[r] = tb[d + 128]; } }
;             else {
; #pragma unroll
;                 for (int r = 0; r < 16; ++r) sc[r] = cfar; }
.LBB0_605:
	s_lshr_b32 s66, s100, 17
	s_add_i32 s66, s61, s66
	s_sub_i32 s66, s63, s66
	s_cmp_lt_u32 s66, 9
	s_cselect_b64 s[68:69], -1, 0
	s_and_b64 s[68:69], s[42:43], s[68:69]
	s_andn2_b64 vcc, exec, s[68:69]
	s_cbranch_vccnz .LBB0_595
	v_mov_b64_e32 v[82:83], v[80:81]
	v_mov_b64_e32 v[80:81], v[78:79]
	v_mov_b64_e32 v[78:79], v[76:77]
	v_mov_b64_e32 v[76:77], v[74:75]
	v_mov_b64_e32 v[74:75], v[72:73]
	v_mov_b64_e32 v[72:73], v[70:71]
	v_mov_b64_e32 v[70:71], v[68:69]
	v_mov_b64_e32 v[68:69], v[66:67]
	s_cmp_gt_u32 s66, 2
	v_mov_b32_e32 v69, v66
	v_mov_b32_e32 v70, v66
	v_mov_b32_e32 v71, v66
	v_mov_b32_e32 v72, v66
	v_mov_b32_e32 v73, v66
	v_mov_b32_e32 v74, v66
	v_mov_b32_e32 v75, v66
	v_mov_b32_e32 v76, v66
	v_mov_b32_e32 v77, v66
	v_mov_b32_e32 v78, v66
	v_mov_b32_e32 v79, v66
	v_mov_b32_e32 v80, v66
	v_mov_b32_e32 v81, v66
	v_mov_b32_e32 v82, v66
	v_mov_b32_e32 v83, v66
	s_cbranch_scc1 .LBB0_594
	v_and_or_b32 v68, s65, 32, v151
	v_lshl_or_b32 v69, s66, 6, v67
	v_sub_u32_e32 v76, v69, v68
	v_xad_u32 v68, v68, -1, v69
	v_min_i32_e32 v68, 0x80, v68
	v_lshl_add_u32 v69, v68, 2, s51
	v_min_i32_e32 v68, 0x82, v76
	v_lshl_add_u32 v71, v68, 2, s51
	v_min_i32_e32 v68, 0x83, v76
	v_lshl_add_u32 v72, v68, 2, s51
	v_min_i32_e32 v68, 0x88, v76
	v_lshl_add_u32 v73, v68, 2, s51
	v_min_i32_e32 v68, 0x89, v76
	v_lshl_add_u32 v74, v68, 2, s51
	v_min_i32_e32 v68, 0x8a, v76
	v_min_i32_e32 v70, 0x80, v76
	v_lshl_add_u32 v75, v68, 2, s51
	v_min_i32_e32 v68, 0x8b, v76
	v_lshl_add_u32 v70, v70, 2, s51
	v_lshl_add_u32 v77, v68, 2, s51
	ds_read_b32 v68, v70 offset:512
	ds_read_b32 v69, v69 offset:512
	ds_read_b32 v70, v71 offset:504
	ds_read_b32 v71, v72 offset:500
	ds_read_b32 v72, v73 offset:480
	ds_read_b32 v73, v74 offset:476
	ds_read_b32 v74, v75 offset:472
	ds_read_b32 v75, v77 offset:468
	v_min_i32_e32 v77, 0x90, v76
	v_min_i32_e32 v78, 0x91, v76
	v_min_i32_e32 v79, 0x92, v76
	v_min_i32_e32 v80, 0x93, v76
	v_min_i32_e32 v81, 0x98, v76
	v_min_i32_e32 v82, 0x99, v76
	v_min_i32_e32 v83, 0x9a, v76
	v_lshl_add_u32 v77, v77, 2, s51
	v_lshl_add_u32 v78, v78, 2, s51
	v_lshl_add_u32 v79, v79, 2, s51
	v_lshl_add_u32 v80, v80, 2, s51
	v_lshl_add_u32 v81, v81, 2, s51
	v_lshl_add_u32 v82, v82, 2, s51
	v_lshl_add_u32 v83, v83, 2, s51
	v_min_i32_e32 v76, 0x9b, v76
	v_lshl_add_u32 v116, v76, 2, s51
	ds_read_b32 v76, v77 offset:448
	ds_read_b32 v77, v78 offset:444
	ds_read_b32 v78, v79 offset:440
	ds_read_b32 v79, v80 offset:436
	ds_read_b32 v80, v81 offset:416
	ds_read_b32 v81, v82 offset:412
	ds_read_b32 v82, v83 offset:408
	ds_read_b32 v83, v116 offset:404
	s_branch .LBB0_594

; __global__ void __launch_bounds__(512, 2) fwd_kernel(Args a) {
	.amdhsa_kernel _Z10fwd_kernel4Args
		.amdhsa_group_segment_fixed_size 0
		.amdhsa_private_segment_fixed_size 0
		.amdhsa_kernarg_size 528
		.amdhsa_user_sgpr_count 2
		.amdhsa_user_sgpr_dispatch_ptr 0
		.amdhsa_user_sgpr_queue_ptr 0
		.amdhsa_user_sgpr_kernarg_segment_ptr 1
		.amdhsa_user_sgpr_dispatch_id 0
		.amdhsa_user_sgpr_kernarg_preload_length 0
		.amdhsa_user_sgpr_kernarg_preload_offset 0
		.amdhsa_user_sgpr_private_segment_size 0
		.amdhsa_uses_dynamic_stack 0
		.amdhsa_enable_private_segment 0
		.amdhsa_system_sgpr_workgroup_id_x 1
		.amdhsa_system_sgpr_workgroup_id_y 0
		.amdhsa_system_sgpr_workgroup_id_z 0
		.amdhsa_system_sgpr_workgroup_info 0
		.amdhsa_system_vgpr_workitem_id 2
		.amdhsa_next_free_vgpr 244
		.amdhsa_next_free_sgpr 102
		.amdhsa_accum_offset 244
		.amdhsa_reserve_vcc 1
		.amdhsa_float_round_mode_32 0
		.amdhsa_float_round_mode_16_64 0
		.amdhsa_float_denorm_mode_32 3
		.amdhsa_float_denorm_mode_16_64 3
		.amdhsa_dx10_clamp 1
		.amdhsa_ieee_mode 1
		.amdhsa_fp16_overflow 0
		.amdhsa_tg_split 0
		.amdhsa_exception_fp_ieee_invalid_op 0
		.amdhsa_exception_fp_denorm_src 0
		.amdhsa_exception_fp_ieee_div_zero 0
		.amdhsa_exception_fp_ieee_overflow 0
		.amdhsa_exception_fp_ieee_underflow 0
		.amdhsa_exception_fp_ieee_inexact 0
		.amdhsa_exception_int_div_zero 0
	.end_amdhsa_kernel

; __global__ void __launch_bounds__(512, 2) fwd_kernel(Args a) {
amdhsa.kernels:
  - .agpr_count:     0
    .args:
      - .offset:         0
        .size:           272
        .value_kind:     by_value
      - .offset:         272
        .size:           4
        .value_kind:     hidden_block_count_x
      - .offset:         276
        .size:           4
        .value_kind:     hidden_block_count_y
      - .offset:         280
        .size:           4
        .value_kind:     hidden_block_count_z
      - .offset:         284
        .size:           2
        .value_kind:     hidden_group_size_x
      - .offset:         286
        .size:           2
        .value_kind:     hidden_group_size_y
      - .offset:         288
        .size:           2
        .value_kind:     hidden_group_size_z
      - .offset:         290
        .size:           2
        .value_kind:     hidden_remainder_x
      - .offset:         292
        .size:           2
        .value_kind:     hidden_remainder_y
      - .offset:         294
        .size:           2
        .value_kind:     hidden_remainder_z
      - .offset:         312
        .size:           8
        .value_kind:     hidden_global_offset_x
      - .offset:         320
        .size:           8
        .value_kind:     hidden_global_offset_y
      - .offset:         328
        .size:           8
        .value_kind:     hidden_global_offset_z
      - .offset:         336
        .size:           2
        .value_kind:     hidden_grid_dims
      - .offset:         360
        .size:           8
        .value_kind:     hidden_multigrid_sync_arg
      - .offset:         392
        .size:           4
        .value_kind:     hidden_dynamic_lds_size
    .group_segment_fixed_size: 0
    .kernarg_segment_align: 8
    .kernarg_segment_size: 528
    .language:       OpenCL C
    .language_version:
      - 2
      - 0
    .max_flat_workgroup_size: 512
    .name:           _Z10fwd_kernel4Args
    .private_segment_fixed_size: 0
    .sgpr_count:     108
    .sgpr_spill_count: 126
    .symbol:         _Z10fwd_kernel4Args.kd
    .uniform_work_group_size: 1
    .uses_dynamic_stack: false
    .vgpr_count:     244
    .vgpr_spill_count: 0
    .wavefront_size: 64
